# v15 = v13 + INPROJ part-1 CU rotation (balances odd-layer z/V^T units) + NA work queue hands out single tasks (shorter tail)
# speedup vs baseline: 1.0047x; 1.0047x over previous
; #define LAS __attribute__((address_space(3)))
; __device__ __forceinline__ void na_fill_table(const PP P, int h, LAS float* tbl, int lane) {
;     const float* rpb = P.in(18) + h * 465;
; #pragma unroll
;     for (int k = 0; k < 16; ++k) {
;         const int e = lane + 64 * k, row = e >> 6, col = e & 63, off = col - 32;
;         float v = 0.f;
;         if (row == 15) v = NEGBIG;
;         else if (off >= -15 && off <= 15) v = rpb[row * 31 + off + 15] * LOG2E;
;         tbl[e] = v;
;     }
; }
; __global__ void __launch_bounds__(NTHREADS, 2) mk_fwd(Params Pk) {
;     ...
;                     for (;;) {
;                         unsigned t0 = 0;
;                         if (lane == 0) t0 = __hip_atomic_fetch_add(ctr, 2u, __ATOMIC_RELAXED, __HIP_MEMORY_SCOPE_AGENT);
;                         t0 = (unsigned)__builtin_amdgcn_readfirstlane((int)t0);
;                         if (t0 >= 1536u) break;
;                         const int tk = (int)(q * 1536u + t0);
;                         na_fill_table(P, (tk >> 2) & 7, (LAS float*)(wl + 9216), lane);
;                         for (int k = 0; k < 2; ++k) na_task4(P, tk + k, (LAS float*)(wl + 9216), lane);
.LBB0_306:
	v_mov_b32_e32 v2, 0
	s_and_saveexec_b64 s[24:25], s[4:5]
	s_cbranch_execz .LBB0_310
	s_mov_b64 s[44:45], exec
	v_mbcnt_lo_u32_b32 v2, s44, 0
	v_mbcnt_hi_u32_b32 v2, s45, v2
	v_cmp_eq_u32_e32 vcc, 0, v2
	s_and_saveexec_b64 s[40:41], vcc
	s_cbranch_execz .LBB0_309
	s_bcnt1_i32_b64 s20, s[44:45]
	v_mov_b32_e32 v3, s20
	global_atomic_add v3, v1, v3, s[22:23] sc0
.LBB0_309:
	s_or_b64 exec, exec, s[40:41]
	s_waitcnt vmcnt(0)
	v_readfirstlane_b32 s20, v3
	s_nop 1
	v_add_u32_e32 v2, s20, v2
.LBB0_310:
	s_or_b64 exec, exec, s[24:25]
	v_readfirstlane_b32 s35, v2
	s_cmpk_gt_u32 s35, 0x5ff
	s_mov_b64 s[24:25], -1
	s_cbranch_scc1 .LBB0_305
	s_load_dwordx2 s[24:25], s[38:39], 0x90
	s_bfe_u32 s20, s35, 0x30002
	s_mulk_i32 s20, 0x744
	v_lshlrev_b32_e32 v2, 2, v202
	s_waitcnt lgkmcnt(0)
	s_add_u32 s24, s24, s20
	s_addc_u32 s25, s25, 0
	v_mov_b32_e32 v3, 0
	v_mov_b32_e32 v4, 0
	v_mov_b32_e32 v5, 0
	v_mov_b32_e32 v6, 0
	v_mov_b32_e32 v7, 0
	v_mov_b32_e32 v8, 0
	v_mov_b32_e32 v9, 0
	v_mov_b32_e32 v10, 0
	v_mov_b32_e32 v11, 0
	v_mov_b32_e32 v12, 0
	v_mov_b32_e32 v13, 0
	v_mov_b32_e32 v14, 0
	v_mov_b32_e32 v15, 0
	v_mov_b32_e32 v16, 0
	v_mov_b32_e32 v17, 0
	s_and_saveexec_b64 s[40:41], s[6:7]
	global_load_dword v3, v2, s[24:25] offset:-68
	global_load_dword v4, v2, s[24:25] offset:56
	global_load_dword v5, v2, s[24:25] offset:180
	global_load_dword v6, v2, s[24:25] offset:304
	global_load_dword v7, v2, s[24:25] offset:428
	global_load_dword v8, v2, s[24:25] offset:552
	global_load_dword v9, v2, s[24:25] offset:676
	global_load_dword v10, v2, s[24:25] offset:800
	global_load_dword v11, v2, s[24:25] offset:924
	global_load_dword v12, v2, s[24:25] offset:1048
	global_load_dword v13, v2, s[24:25] offset:1172
	global_load_dword v14, v2, s[24:25] offset:1296
	global_load_dword v15, v2, s[24:25] offset:1420
	global_load_dword v16, v2, s[24:25] offset:1544
	global_load_dword v17, v2, s[24:25] offset:1668
	s_waitcnt vmcnt(0)
	v_mul_f32_e32 v3, 0x3fb8aa3b, v3
	v_mul_f32_e32 v4, 0x3fb8aa3b, v4
	v_mul_f32_e32 v5, 0x3fb8aa3b, v5
	v_mul_f32_e32 v6, 0x3fb8aa3b, v6
	v_mul_f32_e32 v7, 0x3fb8aa3b, v7
	v_mul_f32_e32 v8, 0x3fb8aa3b, v8
	v_mul_f32_e32 v9, 0x3fb8aa3b, v9
	v_mul_f32_e32 v10, 0x3fb8aa3b, v10
	v_mul_f32_e32 v11, 0x3fb8aa3b, v11
	v_mul_f32_e32 v12, 0x3fb8aa3b, v12
	v_mul_f32_e32 v13, 0x3fb8aa3b, v13
	v_mul_f32_e32 v14, 0x3fb8aa3b, v14
	v_mul_f32_e32 v15, 0x3fb8aa3b, v15
	v_mul_f32_e32 v16, 0x3fb8aa3b, v16
	v_mul_f32_e32 v17, 0x3fb8aa3b, v17
	s_or_b64 exec, exec, s[40:41]
	ds_write2st64_b32 v190, v3, v4 offset0:36 offset1:37
	ds_write2st64_b32 v190, v5, v6 offset0:38 offset1:39
	ds_write2st64_b32 v190, v7, v8 offset0:40 offset1:41
	ds_write2st64_b32 v190, v9, v10 offset0:42 offset1:43
	ds_write2st64_b32 v190, v11, v12 offset0:44 offset1:45
	ds_write2st64_b32 v190, v13, v14 offset0:46 offset1:47
	ds_write2st64_b32 v190, v15, v16 offset0:48 offset1:49
	ds_write2st64_b32 v190, v17, v239 offset0:50 offset1:51
	v_and_b32_e32 v3, 64, v242
	v_xor_b32_e32 v2, 32, v242
	v_add_u32_e32 v3, 64, v3
	v_cmp_lt_i32_e32 vcc, v2, v3
	s_add_i32 s35, s35, s17
	s_mov_b32 s40, 0
	v_cndmask_b32_e32 v2, v242, v2, vcc
	v_lshlrev_b32_e32 v189, 2, v2
	s_mov_b64 s[44:45], 0
	s_branch .LBB0_340

;     __host__ __device__ bool next(int i, Unit& u) const {
;         const long L = (long)i * G + c; if (L >= nwg) return false;
;         int wgid = (int)L; { const int q = nwg / NXCD, r = nwg % NXCD, xcd = wgid % NXCD, off = wgid / NXCD; wgid = (xcd < r ? xcd * (q + 1) : r * (q + 1) + (xcd - r) * q) + off; }
;         const int nig = WGM * nN, gid = wgid / nig, fm = gid * WGM, gsz = (nM - fm) < WGM ? (nM - fm) : WGM;
;         u.pm = fm + ((wgid % nig) % gsz); u.pn = (wgid % nig) / gsz; return true;
; __global__ void __launch_bounds__(NTHREADS, 2) mk_fwd(Params Pk) {
;     ...
;                     const int NV = arg ? 256 : 512;
;                     g = pg8::Gemm{(const bf16_t*)(ws + (arg ? WS_WVO : WS_WVE)), (const bf16_t*)(ws + WS_XN), NV, MT, D};
;                     E = pg8::EpiStore{(bf16_t*)(ws + WS_VT), (size_t)MT, (const float*)((unsigned char*)P.out() + OUT_SSQ) + (size_t)sqi * MT * 16, 1}; S.init(NV, MT, G, cb);
;                 }
;                 pg8::gemm_phase<pg8::EpiStore, pg8::StaticOrder, true, true>(lds, g, S, E);
.LBB0_362:
	s_and_b64 vcc, exec, s[6:7]
	s_cbranch_vccnz .Linp_norot
	s_lshr_b32 s0, s10, 1
	s_add_i32 s34, s34, s0
	s_cmp_ge_u32 s34, s10
	s_cselect_b32 s0, s10, 0
	s_sub_i32 s34, s34, s0
	s_ashr_i32 s65, s34, 31
	s_lshr_b32 s0, s65, 29
	s_add_i32 s1, s34, s0
	s_and_b32 s0, s1, -8
	s_sub_i32 s66, s34, s0
	s_ashr_i32 s67, s1, 3
	s_lshr_b32 s69, s66, 31
